# scan recurrence loop: the y-partial LDS write of a token pair is issued behind the next pair's load burst so no wait covers it
# speedup vs baseline: 1.0812x; 1.0027x over previous
.LBB0_1112:
	s_and_b32 s11, s10, 1
	s_mul_i32 s18, s11, 0x4e00
	s_waitcnt vmcnt(0)
	v_lshl_add_u32 v131, s11, 14, v21
	v_lshl_add_u32 v130, v20, 2, s18
	v_mov_b32_e32 v129, s18
	v_lshl_add_u32 v128, v16, 2, s18
	s_add_i32 s10, s10, 1
	ds_read_b128 v[44:47], v130 offset:0
	ds_read_b128 v[48:51], v130 offset:256
	ds_read_b128 v[52:55], v130 offset:512
	ds_read_b128 v[56:59], v130 offset:768
	ds_read_b128 v[60:63], v130 offset:1024
	ds_read_b128 v[64:67], v130 offset:1280
	ds_read_b128 v[68:71], v130 offset:1536
	ds_read_b128 v[72:75], v130 offset:1792
	ds_read_b128 v[76:79], v130 offset:2048
	ds_read_b128 v[80:83], v129 offset:2432
	ds_read_b128 v[84:87], v129 offset:2448
	ds_read_b32 v89, v128 offset:2304
	ds_read_b32 v91, v128 offset:2368
	ds_read_b128 v[196:199], v130 offset:2496
	ds_read_b128 v[200:203], v130 offset:2752
	ds_read_b128 v[204:207], v130 offset:3008
	ds_read_b128 v[208:211], v130 offset:3264
	ds_read_b128 v[212:215], v130 offset:3520
	ds_read_b128 v[216:219], v130 offset:3776
	ds_read_b128 v[220:223], v130 offset:4032
	ds_read_b128 v[224:227], v130 offset:4288
	ds_read_b128 v[228:231], v130 offset:4544
	ds_read_b128 v[232:235], v129 offset:4928
	ds_read_b128 v[236:239], v129 offset:4944
	ds_read_b32 v241, v128 offset:4800
	ds_read_b32 v243, v128 offset:4864
	s_waitcnt lgkmcnt(13)
	v_pk_mul_f32 v[4:5], v[0:1], v[44:45]
	v_pk_mul_f32 v[6:7], v[0:1], v[48:49]
	v_pk_fma_f32 v[4:5], v[2:3], v[46:47], v[4:5]
	v_pk_fma_f32 v[6:7], v[2:3], v[50:51], v[6:7]
	v_add_f32_e32 v22, v4, v5
	v_add_f32_e32 v42, v6, v7
	v_pk_mul_f32 v[8:9], v[0:1], v[52:53]
	v_add_f32_dpp v22, v22, v22 quad_perm:[1,0,3,2] row_mask:0xf bank_mask:0xf bound_ctrl:1
	v_add_f32_dpp v42, v42, v42 quad_perm:[1,0,3,2] row_mask:0xf bank_mask:0xf bound_ctrl:1
	v_pk_mul_f32 v[10:11], v[2:3], v[54:55]
	v_add_f32_dpp v22, v22, v22 quad_perm:[2,3,0,1] row_mask:0xf bank_mask:0xf bound_ctrl:1
	v_add_f32_dpp v42, v42, v42 quad_perm:[2,3,0,1] row_mask:0xf bank_mask:0xf bound_ctrl:1
	v_pk_mul_f32 v[12:13], v[0:1], v[72:73]
	v_add_f32_dpp v22, v22, v22 row_ror:4 row_mask:0xf bank_mask:0xf bound_ctrl:1
	v_add_f32_dpp v42, v42, v42 row_ror:4 row_mask:0xf bank_mask:0xf bound_ctrl:1
	v_pk_mul_f32 v[14:15], v[0:1], v[76:77]
	v_add_f32_dpp v88, v22, v22 row_ror:8 row_mask:0xf bank_mask:0xf bound_ctrl:1
	v_add_f32_dpp v42, v42, v42 row_ror:8 row_mask:0xf bank_mask:0xf bound_ctrl:1
	v_pk_fma_f32 v[8:9], v[88:89], v[60:61], v[8:9] op_sel:[1,0,0] op_sel_hi:[1,1,1]
	v_pk_fma_f32 v[10:11], v[88:89], v[62:63], v[10:11] op_sel:[1,0,0] op_sel_hi:[1,1,1]
	v_fma_f32 v4, v88, v80, v42
	v_pk_fma_f32 v[8:9], v[90:91], v[68:69], v[8:9] op_sel:[1,0,0] op_sel_hi:[1,1,1]
	v_fma_f32 v90, v89, v81, v4
	v_pk_fma_f32 v[10:11], v[90:91], v[70:71], v[10:11] op_sel:[1,0,0] op_sel_hi:[1,1,1]
	v_pk_fma_f32 v[12:13], v[2:3], v[74:75], v[12:13]
	v_pk_fma_f32 v[14:15], v[2:3], v[78:79], v[14:15]
	v_pk_fma_f32 v[0:1], v[88:89], v[56:57], v[8:9] op_sel:[0,0,0] op_sel_hi:[0,1,1]
	v_pk_fma_f32 v[2:3], v[88:89], v[58:59], v[10:11] op_sel:[0,0,0] op_sel_hi:[0,1,1]
	v_pk_fma_f32 v[0:1], v[90:91], v[64:65], v[0:1] op_sel:[0,0,0] op_sel_hi:[0,1,1]
	v_pk_fma_f32 v[2:3], v[90:91], v[66:67], v[2:3] op_sel:[0,0,0] op_sel_hi:[0,1,1]
	v_pk_fma_f32 v[12:13], v[88:89], v[82:83], v[12:13]
	v_pk_fma_f32 v[14:15], v[90:91], v[86:87], v[14:15]
	v_pk_fma_f32 v[14:15], v[88:89], v[84:85], v[14:15]
	v_add_f32_e32 v126, v12, v13
	v_add_f32_e32 v127, v14, v15
	ds_read_b128 v[44:47], v130 offset:4992
	ds_read_b128 v[48:51], v130 offset:5248
	ds_read_b128 v[52:55], v130 offset:5504
	ds_read_b128 v[56:59], v130 offset:5760
	ds_read_b128 v[60:63], v130 offset:6016
	ds_read_b128 v[64:67], v130 offset:6272
	ds_read_b128 v[68:71], v130 offset:6528
	ds_read_b128 v[72:75], v130 offset:6784
	ds_read_b128 v[76:79], v130 offset:7040
	ds_read_b128 v[80:83], v129 offset:7424
	ds_read_b128 v[84:87], v129 offset:7440
	ds_read_b32 v89, v128 offset:7296
	ds_read_b32 v91, v128 offset:7360
	ds_write2st64_b32 v131, v126, v127 offset0:156 offset1:160
	s_waitcnt lgkmcnt(14)
	v_pk_mul_f32 v[4:5], v[0:1], v[196:197]
	v_pk_mul_f32 v[6:7], v[0:1], v[200:201]
	v_pk_fma_f32 v[4:5], v[2:3], v[198:199], v[4:5]
	v_pk_fma_f32 v[6:7], v[2:3], v[202:203], v[6:7]
	v_add_f32_e32 v22, v4, v5
	v_add_f32_e32 v42, v6, v7
	v_pk_mul_f32 v[8:9], v[0:1], v[204:205]
	v_add_f32_dpp v22, v22, v22 quad_perm:[1,0,3,2] row_mask:0xf bank_mask:0xf bound_ctrl:1
	v_add_f32_dpp v42, v42, v42 quad_perm:[1,0,3,2] row_mask:0xf bank_mask:0xf bound_ctrl:1
	v_pk_mul_f32 v[10:11], v[2:3], v[206:207]
	v_add_f32_dpp v22, v22, v22 quad_perm:[2,3,0,1] row_mask:0xf bank_mask:0xf bound_ctrl:1
	v_add_f32_dpp v42, v42, v42 quad_perm:[2,3,0,1] row_mask:0xf bank_mask:0xf bound_ctrl:1
	v_pk_mul_f32 v[12:13], v[0:1], v[224:225]
	v_add_f32_dpp v22, v22, v22 row_ror:4 row_mask:0xf bank_mask:0xf bound_ctrl:1
	v_add_f32_dpp v42, v42, v42 row_ror:4 row_mask:0xf bank_mask:0xf bound_ctrl:1
	v_pk_mul_f32 v[14:15], v[0:1], v[228:229]
	v_add_f32_dpp v240, v22, v22 row_ror:8 row_mask:0xf bank_mask:0xf bound_ctrl:1
	v_add_f32_dpp v42, v42, v42 row_ror:8 row_mask:0xf bank_mask:0xf bound_ctrl:1
	v_pk_fma_f32 v[8:9], v[240:241], v[212:213], v[8:9] op_sel:[1,0,0] op_sel_hi:[1,1,1]
	v_pk_fma_f32 v[10:11], v[240:241], v[214:215], v[10:11] op_sel:[1,0,0] op_sel_hi:[1,1,1]
	v_fma_f32 v4, v240, v232, v42
	v_pk_fma_f32 v[8:9], v[242:243], v[220:221], v[8:9] op_sel:[1,0,0] op_sel_hi:[1,1,1]
	v_fma_f32 v242, v241, v233, v4
	v_pk_fma_f32 v[10:11], v[242:243], v[222:223], v[10:11] op_sel:[1,0,0] op_sel_hi:[1,1,1]
	v_pk_fma_f32 v[12:13], v[2:3], v[226:227], v[12:13]
	v_pk_fma_f32 v[14:15], v[2:3], v[230:231], v[14:15]
	v_pk_fma_f32 v[0:1], v[240:241], v[208:209], v[8:9] op_sel:[0,0,0] op_sel_hi:[0,1,1]
	v_pk_fma_f32 v[2:3], v[240:241], v[210:211], v[10:11] op_sel:[0,0,0] op_sel_hi:[0,1,1]
	v_pk_fma_f32 v[0:1], v[242:243], v[216:217], v[0:1] op_sel:[0,0,0] op_sel_hi:[0,1,1]
	v_pk_fma_f32 v[2:3], v[242:243], v[218:219], v[2:3] op_sel:[0,0,0] op_sel_hi:[0,1,1]
	v_pk_fma_f32 v[12:13], v[240:241], v[234:235], v[12:13]
	v_pk_fma_f32 v[14:15], v[242:243], v[238:239], v[14:15]
	v_pk_fma_f32 v[14:15], v[240:241], v[236:237], v[14:15]
	v_add_f32_e32 v126, v12, v13
	v_add_f32_e32 v127, v14, v15
	ds_read_b128 v[196:199], v130 offset:7488
	ds_read_b128 v[200:203], v130 offset:7744
	ds_read_b128 v[204:207], v130 offset:8000
	ds_read_b128 v[208:211], v130 offset:8256
	ds_read_b128 v[212:215], v130 offset:8512
	ds_read_b128 v[216:219], v130 offset:8768
	ds_read_b128 v[220:223], v130 offset:9024
	ds_read_b128 v[224:227], v130 offset:9280
	ds_read_b128 v[228:231], v130 offset:9536
	ds_read_b128 v[232:235], v129 offset:9920
	ds_read_b128 v[236:239], v129 offset:9936
	ds_read_b32 v241, v128 offset:9792
	ds_read_b32 v243, v128 offset:9856
	ds_write2st64_b32 v131, v126, v127 offset0:164 offset1:168
	s_waitcnt lgkmcnt(14)
	v_pk_mul_f32 v[4:5], v[0:1], v[44:45]
	v_pk_mul_f32 v[6:7], v[0:1], v[48:49]
	v_pk_fma_f32 v[4:5], v[2:3], v[46:47], v[4:5]
	v_pk_fma_f32 v[6:7], v[2:3], v[50:51], v[6:7]
	v_add_f32_e32 v22, v4, v5
	v_add_f32_e32 v42, v6, v7
	v_pk_mul_f32 v[8:9], v[0:1], v[52:53]
	v_add_f32_dpp v22, v22, v22 quad_perm:[1,0,3,2] row_mask:0xf bank_mask:0xf bound_ctrl:1
	v_add_f32_dpp v42, v42, v42 quad_perm:[1,0,3,2] row_mask:0xf bank_mask:0xf bound_ctrl:1
	v_pk_mul_f32 v[10:11], v[2:3], v[54:55]
	v_add_f32_dpp v22, v22, v22 quad_perm:[2,3,0,1] row_mask:0xf bank_mask:0xf bound_ctrl:1
	v_add_f32_dpp v42, v42, v42 quad_perm:[2,3,0,1] row_mask:0xf bank_mask:0xf bound_ctrl:1
	v_pk_mul_f32 v[12:13], v[0:1], v[72:73]
	v_add_f32_dpp v22, v22, v22 row_ror:4 row_mask:0xf bank_mask:0xf bound_ctrl:1
	v_add_f32_dpp v42, v42, v42 row_ror:4 row_mask:0xf bank_mask:0xf bound_ctrl:1
	v_pk_mul_f32 v[14:15], v[0:1], v[76:77]
	v_add_f32_dpp v88, v22, v22 row_ror:8 row_mask:0xf bank_mask:0xf bound_ctrl:1
	v_add_f32_dpp v42, v42, v42 row_ror:8 row_mask:0xf bank_mask:0xf bound_ctrl:1
	v_pk_fma_f32 v[8:9], v[88:89], v[60:61], v[8:9] op_sel:[1,0,0] op_sel_hi:[1,1,1]
	v_pk_fma_f32 v[10:11], v[88:89], v[62:63], v[10:11] op_sel:[1,0,0] op_sel_hi:[1,1,1]
	v_fma_f32 v4, v88, v80, v42
	v_pk_fma_f32 v[8:9], v[90:91], v[68:69], v[8:9] op_sel:[1,0,0] op_sel_hi:[1,1,1]
	v_fma_f32 v90, v89, v81, v4
	v_pk_fma_f32 v[10:11], v[90:91], v[70:71], v[10:11] op_sel:[1,0,0] op_sel_hi:[1,1,1]
	v_pk_fma_f32 v[12:13], v[2:3], v[74:75], v[12:13]
	v_pk_fma_f32 v[14:15], v[2:3], v[78:79], v[14:15]
	v_pk_fma_f32 v[0:1], v[88:89], v[56:57], v[8:9] op_sel:[0,0,0] op_sel_hi:[0,1,1]
	v_pk_fma_f32 v[2:3], v[88:89], v[58:59], v[10:11] op_sel:[0,0,0] op_sel_hi:[0,1,1]
	v_pk_fma_f32 v[0:1], v[90:91], v[64:65], v[0:1] op_sel:[0,0,0] op_sel_hi:[0,1,1]
	v_pk_fma_f32 v[2:3], v[90:91], v[66:67], v[2:3] op_sel:[0,0,0] op_sel_hi:[0,1,1]
	v_pk_fma_f32 v[12:13], v[88:89], v[82:83], v[12:13]
	v_pk_fma_f32 v[14:15], v[90:91], v[86:87], v[14:15]
	v_pk_fma_f32 v[14:15], v[88:89], v[84:85], v[14:15]
	v_add_f32_e32 v126, v12, v13
	v_add_f32_e32 v127, v14, v15
	ds_read_b128 v[44:47], v130 offset:9984
	ds_read_b128 v[48:51], v130 offset:10240
	ds_read_b128 v[52:55], v130 offset:10496
	ds_read_b128 v[56:59], v130 offset:10752
	ds_read_b128 v[60:63], v130 offset:11008
	ds_read_b128 v[64:67], v130 offset:11264
	ds_read_b128 v[68:71], v130 offset:11520
	ds_read_b128 v[72:75], v130 offset:11776
	ds_read_b128 v[76:79], v130 offset:12032
	ds_read_b128 v[80:83], v129 offset:12416
	ds_read_b128 v[84:87], v129 offset:12432
	ds_read_b32 v89, v128 offset:12288
	ds_read_b32 v91, v128 offset:12352
	ds_write2st64_b32 v131, v126, v127 offset0:172 offset1:176
	s_waitcnt lgkmcnt(14)
	v_pk_mul_f32 v[4:5], v[0:1], v[196:197]
	v_pk_mul_f32 v[6:7], v[0:1], v[200:201]
	v_pk_fma_f32 v[4:5], v[2:3], v[198:199], v[4:5]
	v_pk_fma_f32 v[6:7], v[2:3], v[202:203], v[6:7]
	v_add_f32_e32 v22, v4, v5
	v_add_f32_e32 v42, v6, v7
	v_pk_mul_f32 v[8:9], v[0:1], v[204:205]
	v_add_f32_dpp v22, v22, v22 quad_perm:[1,0,3,2] row_mask:0xf bank_mask:0xf bound_ctrl:1
	v_add_f32_dpp v42, v42, v42 quad_perm:[1,0,3,2] row_mask:0xf bank_mask:0xf bound_ctrl:1
	v_pk_mul_f32 v[10:11], v[2:3], v[206:207]
	v_add_f32_dpp v22, v22, v22 quad_perm:[2,3,0,1] row_mask:0xf bank_mask:0xf bound_ctrl:1
	v_add_f32_dpp v42, v42, v42 quad_perm:[2,3,0,1] row_mask:0xf bank_mask:0xf bound_ctrl:1
	v_pk_mul_f32 v[12:13], v[0:1], v[224:225]
	v_add_f32_dpp v22, v22, v22 row_ror:4 row_mask:0xf bank_mask:0xf bound_ctrl:1
	v_add_f32_dpp v42, v42, v42 row_ror:4 row_mask:0xf bank_mask:0xf bound_ctrl:1
	v_pk_mul_f32 v[14:15], v[0:1], v[228:229]
	v_add_f32_dpp v240, v22, v22 row_ror:8 row_mask:0xf bank_mask:0xf bound_ctrl:1
	v_add_f32_dpp v42, v42, v42 row_ror:8 row_mask:0xf bank_mask:0xf bound_ctrl:1
	v_pk_fma_f32 v[8:9], v[240:241], v[212:213], v[8:9] op_sel:[1,0,0] op_sel_hi:[1,1,1]
	v_pk_fma_f32 v[10:11], v[240:241], v[214:215], v[10:11] op_sel:[1,0,0] op_sel_hi:[1,1,1]
	v_fma_f32 v4, v240, v232, v42
	v_pk_fma_f32 v[8:9], v[242:243], v[220:221], v[8:9] op_sel:[1,0,0] op_sel_hi:[1,1,1]
	v_fma_f32 v242, v241, v233, v4
	v_pk_fma_f32 v[10:11], v[242:243], v[222:223], v[10:11] op_sel:[1,0,0] op_sel_hi:[1,1,1]
	v_pk_fma_f32 v[12:13], v[2:3], v[226:227], v[12:13]
	v_pk_fma_f32 v[14:15], v[2:3], v[230:231], v[14:15]
	v_pk_fma_f32 v[0:1], v[240:241], v[208:209], v[8:9] op_sel:[0,0,0] op_sel_hi:[0,1,1]
	v_pk_fma_f32 v[2:3], v[240:241], v[210:211], v[10:11] op_sel:[0,0,0] op_sel_hi:[0,1,1]
	v_pk_fma_f32 v[0:1], v[242:243], v[216:217], v[0:1] op_sel:[0,0,0] op_sel_hi:[0,1,1]
	v_pk_fma_f32 v[2:3], v[242:243], v[218:219], v[2:3] op_sel:[0,0,0] op_sel_hi:[0,1,1]
	v_pk_fma_f32 v[12:13], v[240:241], v[234:235], v[12:13]
	v_pk_fma_f32 v[14:15], v[242:243], v[238:239], v[14:15]
	v_pk_fma_f32 v[14:15], v[240:241], v[236:237], v[14:15]
	v_add_f32_e32 v126, v12, v13
	v_add_f32_e32 v127, v14, v15
	ds_read_b128 v[196:199], v130 offset:12480
	ds_read_b128 v[200:203], v130 offset:12736
	ds_read_b128 v[204:207], v130 offset:12992
	ds_read_b128 v[208:211], v130 offset:13248
	ds_read_b128 v[212:215], v130 offset:13504
	ds_read_b128 v[216:219], v130 offset:13760
	ds_read_b128 v[220:223], v130 offset:14016
	ds_read_b128 v[224:227], v130 offset:14272
	ds_read_b128 v[228:231], v130 offset:14528
	ds_read_b128 v[232:235], v129 offset:14912
	ds_read_b128 v[236:239], v129 offset:14928
	ds_read_b32 v241, v128 offset:14784
	ds_read_b32 v243, v128 offset:14848
	ds_write2st64_b32 v131, v126, v127 offset0:180 offset1:184
	s_waitcnt lgkmcnt(14)
	v_pk_mul_f32 v[4:5], v[0:1], v[44:45]
	v_pk_mul_f32 v[6:7], v[0:1], v[48:49]
	v_pk_fma_f32 v[4:5], v[2:3], v[46:47], v[4:5]
	v_pk_fma_f32 v[6:7], v[2:3], v[50:51], v[6:7]
	v_add_f32_e32 v22, v4, v5
	v_add_f32_e32 v42, v6, v7
	v_pk_mul_f32 v[8:9], v[0:1], v[52:53]
	v_add_f32_dpp v22, v22, v22 quad_perm:[1,0,3,2] row_mask:0xf bank_mask:0xf bound_ctrl:1
	v_add_f32_dpp v42, v42, v42 quad_perm:[1,0,3,2] row_mask:0xf bank_mask:0xf bound_ctrl:1
	v_pk_mul_f32 v[10:11], v[2:3], v[54:55]
	v_add_f32_dpp v22, v22, v22 quad_perm:[2,3,0,1] row_mask:0xf bank_mask:0xf bound_ctrl:1
	v_add_f32_dpp v42, v42, v42 quad_perm:[2,3,0,1] row_mask:0xf bank_mask:0xf bound_ctrl:1
	v_pk_mul_f32 v[12:13], v[0:1], v[72:73]
	v_add_f32_dpp v22, v22, v22 row_ror:4 row_mask:0xf bank_mask:0xf bound_ctrl:1
	v_add_f32_dpp v42, v42, v42 row_ror:4 row_mask:0xf bank_mask:0xf bound_ctrl:1
	v_pk_mul_f32 v[14:15], v[0:1], v[76:77]
	v_add_f32_dpp v88, v22, v22 row_ror:8 row_mask:0xf bank_mask:0xf bound_ctrl:1
	v_add_f32_dpp v42, v42, v42 row_ror:8 row_mask:0xf bank_mask:0xf bound_ctrl:1
	v_pk_fma_f32 v[8:9], v[88:89], v[60:61], v[8:9] op_sel:[1,0,0] op_sel_hi:[1,1,1]
	v_pk_fma_f32 v[10:11], v[88:89], v[62:63], v[10:11] op_sel:[1,0,0] op_sel_hi:[1,1,1]
	v_fma_f32 v4, v88, v80, v42
	v_pk_fma_f32 v[8:9], v[90:91], v[68:69], v[8:9] op_sel:[1,0,0] op_sel_hi:[1,1,1]
	v_fma_f32 v90, v89, v81, v4
	v_pk_fma_f32 v[10:11], v[90:91], v[70:71], v[10:11] op_sel:[1,0,0] op_sel_hi:[1,1,1]
	v_pk_fma_f32 v[12:13], v[2:3], v[74:75], v[12:13]
	v_pk_fma_f32 v[14:15], v[2:3], v[78:79], v[14:15]
	v_pk_fma_f32 v[0:1], v[88:89], v[56:57], v[8:9] op_sel:[0,0,0] op_sel_hi:[0,1,1]
	v_pk_fma_f32 v[2:3], v[88:89], v[58:59], v[10:11] op_sel:[0,0,0] op_sel_hi:[0,1,1]
	v_pk_fma_f32 v[0:1], v[90:91], v[64:65], v[0:1] op_sel:[0,0,0] op_sel_hi:[0,1,1]
	v_pk_fma_f32 v[2:3], v[90:91], v[66:67], v[2:3] op_sel:[0,0,0] op_sel_hi:[0,1,1]
	v_pk_fma_f32 v[12:13], v[88:89], v[82:83], v[12:13]
	v_pk_fma_f32 v[14:15], v[90:91], v[86:87], v[14:15]
	v_pk_fma_f32 v[14:15], v[88:89], v[84:85], v[14:15]
	v_add_f32_e32 v126, v12, v13
	v_add_f32_e32 v127, v14, v15
	ds_read_b128 v[44:47], v130 offset:14976
	ds_read_b128 v[48:51], v130 offset:15232
	ds_read_b128 v[52:55], v130 offset:15488
	ds_read_b128 v[56:59], v130 offset:15744
	ds_read_b128 v[60:63], v130 offset:16000
	ds_read_b128 v[64:67], v130 offset:16256
	ds_read_b128 v[68:71], v130 offset:16512
	ds_read_b128 v[72:75], v130 offset:16768
	ds_read_b128 v[76:79], v130 offset:17024
	ds_read_b128 v[80:83], v129 offset:17408
	ds_read_b128 v[84:87], v129 offset:17424
	ds_read_b32 v89, v128 offset:17280
	ds_read_b32 v91, v128 offset:17344
	ds_write2st64_b32 v131, v126, v127 offset0:188 offset1:192
	s_waitcnt lgkmcnt(14)
	v_pk_mul_f32 v[4:5], v[0:1], v[196:197]
	v_pk_mul_f32 v[6:7], v[0:1], v[200:201]
	v_pk_fma_f32 v[4:5], v[2:3], v[198:199], v[4:5]
	v_pk_fma_f32 v[6:7], v[2:3], v[202:203], v[6:7]
	v_add_f32_e32 v22, v4, v5
	v_add_f32_e32 v42, v6, v7
	v_pk_mul_f32 v[8:9], v[0:1], v[204:205]
	v_add_f32_dpp v22, v22, v22 quad_perm:[1,0,3,2] row_mask:0xf bank_mask:0xf bound_ctrl:1
	v_add_f32_dpp v42, v42, v42 quad_perm:[1,0,3,2] row_mask:0xf bank_mask:0xf bound_ctrl:1
	v_pk_mul_f32 v[10:11], v[2:3], v[206:207]
	v_add_f32_dpp v22, v22, v22 quad_perm:[2,3,0,1] row_mask:0xf bank_mask:0xf bound_ctrl:1
	v_add_f32_dpp v42, v42, v42 quad_perm:[2,3,0,1] row_mask:0xf bank_mask:0xf bound_ctrl:1
	v_pk_mul_f32 v[12:13], v[0:1], v[224:225]
	v_add_f32_dpp v22, v22, v22 row_ror:4 row_mask:0xf bank_mask:0xf bound_ctrl:1
	v_add_f32_dpp v42, v42, v42 row_ror:4 row_mask:0xf bank_mask:0xf bound_ctrl:1
	v_pk_mul_f32 v[14:15], v[0:1], v[228:229]
	v_add_f32_dpp v240, v22, v22 row_ror:8 row_mask:0xf bank_mask:0xf bound_ctrl:1
	v_add_f32_dpp v42, v42, v42 row_ror:8 row_mask:0xf bank_mask:0xf bound_ctrl:1
	v_pk_fma_f32 v[8:9], v[240:241], v[212:213], v[8:9] op_sel:[1,0,0] op_sel_hi:[1,1,1]
	v_pk_fma_f32 v[10:11], v[240:241], v[214:215], v[10:11] op_sel:[1,0,0] op_sel_hi:[1,1,1]
	v_fma_f32 v4, v240, v232, v42
	v_pk_fma_f32 v[8:9], v[242:243], v[220:221], v[8:9] op_sel:[1,0,0] op_sel_hi:[1,1,1]
	v_fma_f32 v242, v241, v233, v4
	v_pk_fma_f32 v[10:11], v[242:243], v[222:223], v[10:11] op_sel:[1,0,0] op_sel_hi:[1,1,1]
	v_pk_fma_f32 v[12:13], v[2:3], v[226:227], v[12:13]
	v_pk_fma_f32 v[14:15], v[2:3], v[230:231], v[14:15]
	v_pk_fma_f32 v[0:1], v[240:241], v[208:209], v[8:9] op_sel:[0,0,0] op_sel_hi:[0,1,1]
	v_pk_fma_f32 v[2:3], v[240:241], v[210:211], v[10:11] op_sel:[0,0,0] op_sel_hi:[0,1,1]
	v_pk_fma_f32 v[0:1], v[242:243], v[216:217], v[0:1] op_sel:[0,0,0] op_sel_hi:[0,1,1]
	v_pk_fma_f32 v[2:3], v[242:243], v[218:219], v[2:3] op_sel:[0,0,0] op_sel_hi:[0,1,1]
	v_pk_fma_f32 v[12:13], v[240:241], v[234:235], v[12:13]
	v_pk_fma_f32 v[14:15], v[242:243], v[238:239], v[14:15]
	v_pk_fma_f32 v[14:15], v[240:241], v[236:237], v[14:15]
	v_add_f32_e32 v126, v12, v13
	v_add_f32_e32 v127, v14, v15
	ds_read_b128 v[196:199], v130 offset:17472
	ds_read_b128 v[200:203], v130 offset:17728
	ds_read_b128 v[204:207], v130 offset:17984
	ds_read_b128 v[208:211], v130 offset:18240
	ds_read_b128 v[212:215], v130 offset:18496
	ds_read_b128 v[216:219], v130 offset:18752
	ds_read_b128 v[220:223], v130 offset:19008
	ds_read_b128 v[224:227], v130 offset:19264
	ds_read_b128 v[228:231], v130 offset:19520
	ds_read_b128 v[232:235], v129 offset:19904
	ds_read_b128 v[236:239], v129 offset:19920
	ds_read_b32 v241, v128 offset:19776
	ds_read_b32 v243, v128 offset:19840
	ds_write2st64_b32 v131, v126, v127 offset0:196 offset1:200
	s_waitcnt lgkmcnt(14)
	v_pk_mul_f32 v[4:5], v[0:1], v[44:45]
	v_pk_mul_f32 v[6:7], v[0:1], v[48:49]
	v_pk_fma_f32 v[4:5], v[2:3], v[46:47], v[4:5]
	v_pk_fma_f32 v[6:7], v[2:3], v[50:51], v[6:7]
	v_add_f32_e32 v22, v4, v5
	v_add_f32_e32 v42, v6, v7
	v_pk_mul_f32 v[8:9], v[0:1], v[52:53]
	v_add_f32_dpp v22, v22, v22 quad_perm:[1,0,3,2] row_mask:0xf bank_mask:0xf bound_ctrl:1
	v_add_f32_dpp v42, v42, v42 quad_perm:[1,0,3,2] row_mask:0xf bank_mask:0xf bound_ctrl:1
	v_pk_mul_f32 v[10:11], v[2:3], v[54:55]
	v_add_f32_dpp v22, v22, v22 quad_perm:[2,3,0,1] row_mask:0xf bank_mask:0xf bound_ctrl:1
	v_add_f32_dpp v42, v42, v42 quad_perm:[2,3,0,1] row_mask:0xf bank_mask:0xf bound_ctrl:1
	v_pk_mul_f32 v[12:13], v[0:1], v[72:73]
	v_add_f32_dpp v22, v22, v22 row_ror:4 row_mask:0xf bank_mask:0xf bound_ctrl:1
	v_add_f32_dpp v42, v42, v42 row_ror:4 row_mask:0xf bank_mask:0xf bound_ctrl:1
	v_pk_mul_f32 v[14:15], v[0:1], v[76:77]
	v_add_f32_dpp v88, v22, v22 row_ror:8 row_mask:0xf bank_mask:0xf bound_ctrl:1
	v_add_f32_dpp v42, v42, v42 row_ror:8 row_mask:0xf bank_mask:0xf bound_ctrl:1
	v_pk_fma_f32 v[8:9], v[88:89], v[60:61], v[8:9] op_sel:[1,0,0] op_sel_hi:[1,1,1]
	v_pk_fma_f32 v[10:11], v[88:89], v[62:63], v[10:11] op_sel:[1,0,0] op_sel_hi:[1,1,1]
	v_fma_f32 v4, v88, v80, v42
	v_pk_fma_f32 v[8:9], v[90:91], v[68:69], v[8:9] op_sel:[1,0,0] op_sel_hi:[1,1,1]
	v_fma_f32 v90, v89, v81, v4
	v_pk_fma_f32 v[10:11], v[90:91], v[70:71], v[10:11] op_sel:[1,0,0] op_sel_hi:[1,1,1]
	v_pk_fma_f32 v[12:13], v[2:3], v[74:75], v[12:13]
	v_pk_fma_f32 v[14:15], v[2:3], v[78:79], v[14:15]
	v_pk_fma_f32 v[0:1], v[88:89], v[56:57], v[8:9] op_sel:[0,0,0] op_sel_hi:[0,1,1]
	v_pk_fma_f32 v[2:3], v[88:89], v[58:59], v[10:11] op_sel:[0,0,0] op_sel_hi:[0,1,1]
	v_pk_fma_f32 v[0:1], v[90:91], v[64:65], v[0:1] op_sel:[0,0,0] op_sel_hi:[0,1,1]
	v_pk_fma_f32 v[2:3], v[90:91], v[66:67], v[2:3] op_sel:[0,0,0] op_sel_hi:[0,1,1]
	v_pk_fma_f32 v[12:13], v[88:89], v[82:83], v[12:13]
	v_pk_fma_f32 v[14:15], v[90:91], v[86:87], v[14:15]
	v_pk_fma_f32 v[14:15], v[88:89], v[84:85], v[14:15]
	v_add_f32_e32 v126, v12, v13
	v_add_f32_e32 v127, v14, v15
	ds_write2st64_b32 v131, v126, v127 offset0:204 offset1:208
	s_waitcnt lgkmcnt(1)
	v_pk_mul_f32 v[4:5], v[0:1], v[196:197]
	v_pk_mul_f32 v[6:7], v[0:1], v[200:201]
	v_pk_fma_f32 v[4:5], v[2:3], v[198:199], v[4:5]
	v_pk_fma_f32 v[6:7], v[2:3], v[202:203], v[6:7]
	v_add_f32_e32 v22, v4, v5
	v_add_f32_e32 v42, v6, v7
	v_pk_mul_f32 v[8:9], v[0:1], v[204:205]
	v_add_f32_dpp v22, v22, v22 quad_perm:[1,0,3,2] row_mask:0xf bank_mask:0xf bound_ctrl:1
	v_add_f32_dpp v42, v42, v42 quad_perm:[1,0,3,2] row_mask:0xf bank_mask:0xf bound_ctrl:1
	v_pk_mul_f32 v[10:11], v[2:3], v[206:207]
	v_add_f32_dpp v22, v22, v22 quad_perm:[2,3,0,1] row_mask:0xf bank_mask:0xf bound_ctrl:1
	v_add_f32_dpp v42, v42, v42 quad_perm:[2,3,0,1] row_mask:0xf bank_mask:0xf bound_ctrl:1
	v_pk_mul_f32 v[12:13], v[0:1], v[224:225]
	v_add_f32_dpp v22, v22, v22 row_ror:4 row_mask:0xf bank_mask:0xf bound_ctrl:1
	v_add_f32_dpp v42, v42, v42 row_ror:4 row_mask:0xf bank_mask:0xf bound_ctrl:1
	v_pk_mul_f32 v[14:15], v[0:1], v[228:229]
	v_add_f32_dpp v240, v22, v22 row_ror:8 row_mask:0xf bank_mask:0xf bound_ctrl:1
	v_add_f32_dpp v42, v42, v42 row_ror:8 row_mask:0xf bank_mask:0xf bound_ctrl:1
	v_pk_fma_f32 v[8:9], v[240:241], v[212:213], v[8:9] op_sel:[1,0,0] op_sel_hi:[1,1,1]
	v_pk_fma_f32 v[10:11], v[240:241], v[214:215], v[10:11] op_sel:[1,0,0] op_sel_hi:[1,1,1]
	v_fma_f32 v4, v240, v232, v42
	v_pk_fma_f32 v[8:9], v[242:243], v[220:221], v[8:9] op_sel:[1,0,0] op_sel_hi:[1,1,1]
	v_fma_f32 v242, v241, v233, v4
	v_pk_fma_f32 v[10:11], v[242:243], v[222:223], v[10:11] op_sel:[1,0,0] op_sel_hi:[1,1,1]
	v_pk_fma_f32 v[12:13], v[2:3], v[226:227], v[12:13]
	v_pk_fma_f32 v[14:15], v[2:3], v[230:231], v[14:15]
	v_pk_fma_f32 v[0:1], v[240:241], v[208:209], v[8:9] op_sel:[0,0,0] op_sel_hi:[0,1,1]
	v_pk_fma_f32 v[2:3], v[240:241], v[210:211], v[10:11] op_sel:[0,0,0] op_sel_hi:[0,1,1]
	v_pk_fma_f32 v[0:1], v[242:243], v[216:217], v[0:1] op_sel:[0,0,0] op_sel_hi:[0,1,1]
	v_pk_fma_f32 v[2:3], v[242:243], v[218:219], v[2:3] op_sel:[0,0,0] op_sel_hi:[0,1,1]
	v_pk_fma_f32 v[12:13], v[240:241], v[234:235], v[12:13]
	v_pk_fma_f32 v[14:15], v[242:243], v[238:239], v[14:15]
	v_pk_fma_f32 v[14:15], v[240:241], v[236:237], v[14:15]
	v_add_f32_e32 v126, v12, v13
	v_add_f32_e32 v127, v14, v15
	ds_write2st64_b32 v131, v126, v127 offset0:212 offset1:216
